# mLSTM chunk loop: packed f32 VOP3P ops split into scalar pairs as well
# baseline (speedup 1.0000x reference)
.LBB0_325:
	v_sub_f32_e32 v32, v88, v210
	v_mul_f32_e32 v32, 0x3fb8aa3b, v32
	v_exp_f32_e32 v88, v32
	v_cvt_pk_bf16_f32 v32, v58, v59
	v_cvt_pk_bf16_f32 v33, v56, v57
	v_cvt_pk_bf16_f32 v34, v60, v61
	v_cvt_pk_bf16_f32 v35, v62, v63
	s_add_u32 s44, s44, 0x20000
	v_mul_f32_e32 v2, v2, v88
	v_mul_f32_e32 v3, v3, v88
	v_mul_f32_e32 v0, v0, v88
	v_mul_f32_e32 v1, v1, v88
	v_mul_f32_e32 v6, v6, v88
	v_mul_f32_e32 v7, v7, v88
	v_mul_f32_e32 v4, v4, v88
	v_mul_f32_e32 v5, v5, v88
	v_mul_f32_e32 v10, v10, v88
	v_mul_f32_e32 v11, v11, v88
	v_mul_f32_e32 v8, v8, v88
	v_mul_f32_e32 v9, v9, v88
	v_mul_f32_e32 v14, v14, v88
	v_mul_f32_e32 v15, v15, v88
	v_mul_f32_e32 v12, v12, v88
	v_mul_f32_e32 v13, v13, v88
	v_mul_f32_e32 v18, v18, v88
	v_mul_f32_e32 v19, v19, v88
	v_mul_f32_e32 v16, v16, v88
	v_mul_f32_e32 v17, v17, v88
	v_mul_f32_e32 v22, v22, v88
	v_mul_f32_e32 v23, v23, v88
	v_mul_f32_e32 v20, v20, v88
	v_mul_f32_e32 v21, v21, v88
	v_mul_f32_e32 v26, v26, v88
	v_mul_f32_e32 v27, v27, v88
	v_mul_f32_e32 v24, v24, v88
	v_mul_f32_e32 v25, v25, v88
	v_mul_f32_e32 v30, v30, v88
	v_mul_f32_e32 v31, v31, v88
	v_mul_f32_e32 v28, v28, v88
	v_mul_f32_e32 v29, v29, v88
	s_waitcnt vmcnt(15)
	v_mfma_f32_16x16x32_bf16 v[0:3], v[124:127], v[52:55], v[0:3]
	s_addc_u32 s45, s45, 0
	s_addk_i32 s76, 0xc0
	s_addk_i32 s24, 0x400
	s_waitcnt vmcnt(13)
	v_mfma_f32_16x16x32_bf16 v[4:7], v[112:115], v[52:55], v[4:7]
	v_lshl_add_u64 v[162:163], v[162:163], 0, s[14:15]
	v_add_u32_e32 v156, 64, v156
	v_lshl_add_u64 v[172:173], v[172:173], 0, s[16:17]
	s_waitcnt vmcnt(11)
	v_mfma_f32_16x16x32_bf16 v[8:11], v[92:95], v[52:55], v[8:11]
	v_lshl_add_u64 v[174:175], v[174:175], 0, s[18:19]
	v_lshl_add_u64 v[176:177], v[176:177], 0, s[16:17]
	s_cmp_lg_u32 s44, 0x800000
	s_waitcnt vmcnt(9)
	v_mfma_f32_16x16x32_bf16 v[12:15], v[80:83], v[52:55], v[12:15]
	v_mov_b32_e32 v124, v212
	v_mov_b32_e32 v215, v213
	v_mov_b32_e32 v214, v211
	s_waitcnt vmcnt(7)
	v_mfma_f32_16x16x32_bf16 v[16:19], v[72:75], v[52:55], v[16:19]
	s_waitcnt vmcnt(5)
	v_mfma_f32_16x16x32_bf16 v[20:23], v[68:71], v[52:55], v[20:23]
	s_waitcnt vmcnt(3)
	v_mfma_f32_16x16x32_bf16 v[24:27], v[48:51], v[52:55], v[24:27]
	s_waitcnt vmcnt(1)
	v_mfma_f32_16x16x32_bf16 v[28:31], v[44:47], v[52:55], v[28:31]
	v_mfma_f32_16x16x32_bf16 v[0:3], v[120:123], v[32:35], v[0:3]
	v_mfma_f32_16x16x32_bf16 v[4:7], v[116:119], v[32:35], v[4:7]
	v_mfma_f32_16x16x32_bf16 v[8:11], v[96:99], v[32:35], v[8:11]
	v_mfma_f32_16x16x32_bf16 v[12:15], v[84:87], v[32:35], v[12:15]
	v_mfma_f32_16x16x32_bf16 v[16:19], v[76:79], v[32:35], v[16:19]
	v_mfma_f32_16x16x32_bf16 v[20:23], v[64:67], v[32:35], v[20:23]
	v_mfma_f32_16x16x32_bf16 v[24:27], v[40:43], v[32:35], v[24:27]
	s_waitcnt vmcnt(0)
	v_mfma_f32_16x16x32_bf16 v[28:31], v[36:39], v[32:35], v[28:31]
	s_cbranch_scc0 .LBB0_317

.LBB0_334:
	s_waitcnt vmcnt(19)
	v_mfma_f32_16x16x32_bf16 v[96:99], v[128:131], v[96:99], 0
	v_max_f32_e32 v125, v215, v215
	v_max_f32_e32 v126, v210, v210
	v_max_f32_e32 v218, v126, v125
	s_waitcnt vmcnt(16)
	v_mfma_f32_16x16x32_bf16 v[96:99], v[140:143], v[120:123], v[96:99]
	v_sub_f32_e32 v125, v210, v218
	v_mul_f32_e32 v125, 0x3fb8aa3b, v125
	v_add_f32_e32 v124, v124, v218
	v_mfma_f32_16x16x32_bf16 v[96:99], v[144:147], v[116:119], v[96:99]
	ds_bpermute_b32 v116, v190, v218
	ds_bpermute_b32 v117, v190, v215
	v_exp_f32_e32 v219, v125
	v_mul_f32_e32 v120, 0xbfb8aa3b, v124
	v_exp_f32_e32 v220, v120
	s_waitcnt vmcnt(0)
	v_mfma_f32_16x16x32_bf16 v[92:95], v[52:55], v[92:95], 0
	s_and_b64 vcc, exec, s[10:11]
	s_mov_b64 s[48:49], -1
	v_mfma_f32_16x16x32_bf16 v[112:115], v[148:151], v[112:115], v[96:99]
	s_nop 2
	ds_bpermute_b32 v98, v190, v219
	s_waitcnt lgkmcnt(1)
	v_sub_f32_e32 v97, v117, v116
	v_mul_f32_e32 v97, 0x3fb8aa3b, v97
	ds_bpermute_b32 v96, v190, v220
	v_exp_f32_e32 v116, v97
	v_mfma_f32_16x16x32_bf16 v[84:87], v[32:35], v[84:87], v[92:95]
	s_waitcnt lgkmcnt(1)
	v_mul_f32_e32 v114, v114, v98
	v_mul_f32_e32 v115, v115, v98
	s_nop 0
	v_mul_f32_e32 v92, v112, v98
	v_mul_f32_e32 v93, v113, v98
	s_nop 3
	v_fma_f32 v86, v116, v86, v114
	v_fma_f32 v87, v116, v87, v115
	v_fma_f32 v84, v116, v84, v92
	v_fma_f32 v85, v116, v85, v93
	s_cbranch_vccnz .LBB0_336
	v_lshl_add_u64 v[92:93], v[170:171], 0, s[44:45]
	s_mov_b64 s[48:49], 0
	global_store_dwordx4 v[92:93], v[84:87], off

.LBB0_340:
	v_mfma_f32_16x16x32_bf16 v[76:79], v[128:131], v[76:79], 0
	s_and_b64 vcc, exec, s[10:11]
	s_mov_b64 s[48:49], -1
	v_mfma_f32_16x16x32_bf16 v[76:79], v[140:143], v[80:83], v[76:79]
	ds_bpermute_b32 v80, v191, v218
	v_mfma_f32_16x16x32_bf16 v[74:77], v[144:147], v[72:75], v[76:79]
	ds_bpermute_b32 v73, v191, v215
	ds_bpermute_b32 v72, v191, v220
	s_waitcnt lgkmcnt(1)
	v_sub_f32_e32 v73, v73, v80
	v_mfma_f32_16x16x32_bf16 v[64:67], v[52:55], v[64:67], 0
	v_mul_f32_e32 v73, 0x3fb8aa3b, v73
	v_mfma_f32_16x16x32_bf16 v[68:71], v[148:151], v[68:71], v[74:77]
	s_nop 2
	ds_bpermute_b32 v74, v191, v219
	v_exp_f32_e32 v76, v73
	v_mfma_f32_16x16x32_bf16 v[48:51], v[32:35], v[48:51], v[64:67]
	s_waitcnt lgkmcnt(0)
	s_nop 0
	v_mul_f32_e32 v70, v70, v74
	v_mul_f32_e32 v71, v71, v74
	v_mul_f32_e32 v68, v68, v74
	v_mul_f32_e32 v69, v69, v74
	s_nop 3
	v_fma_f32 v48, v76, v48, v68
	v_fma_f32 v49, v76, v49, v69
	v_fma_f32 v50, v76, v50, v70
	v_fma_f32 v51, v76, v51, v71
	s_cbranch_vccnz .LBB0_342
	v_lshl_add_u64 v[64:65], v[168:169], 0, s[44:45]
	s_mov_b64 s[48:49], 0
	global_store_dwordx4 v[64:65], v[48:51], off

.LBB0_346:
	v_add_co_u32_e32 v48, vcc, 0x182e0000, v178
	v_mfma_f32_16x16x32_bf16 v[222:225], v[128:131], v[40:43], 0
	s_nop 0
	v_addc_co_u32_e32 v49, vcc, 0, v179, vcc
	global_load_dwordx4 v[124:127], v[48:49], off offset:2048
	global_load_dwordx4 v[120:123], v[48:49], off offset:3072
	v_add_co_u32_e32 v48, vcc, 0x182e1000, v178
	v_mfma_f32_16x16x32_bf16 v[36:39], v[140:143], v[36:39], v[222:225]
	s_nop 0
	v_addc_co_u32_e32 v49, vcc, 0, v179, vcc
	global_load_dwordx4 v[112:115], v[48:49], off
	global_load_dwordx4 v[116:119], v[48:49], off offset:1024
	global_load_dwordx4 v[92:95], v[48:49], off offset:2048
	global_load_dwordx4 v[96:99], v[48:49], off offset:3072
	v_add_co_u32_e32 v48, vcc, 0x182e2000, v178
	v_mfma_f32_16x16x32_bf16 v[222:225], v[144:147], v[44:47], v[36:39]
	s_nop 0
	v_addc_co_u32_e32 v49, vcc, 0, v179, vcc
	v_add_co_u32_e32 v226, vcc, 0x182e3000, v178
	global_load_dwordx4 v[80:83], v[48:49], off
	global_load_dwordx4 v[84:87], v[48:49], off offset:1024
	global_load_dwordx4 v[72:75], v[48:49], off offset:2048
	global_load_dwordx4 v[76:79], v[48:49], off offset:3072
	v_addc_co_u32_e32 v227, vcc, 0, v179, vcc
	v_add_co_u32_e32 v178, vcc, 0x182e4000, v178
	global_load_dwordx4 v[68:71], v[226:227], off
	global_load_dwordx4 v[64:67], v[226:227], off offset:1024
	v_addc_co_u32_e32 v179, vcc, 0, v179, vcc
	global_load_dwordx4 v[48:51], v[226:227], off offset:2048
	global_load_dwordx4 v[40:43], v[226:227], off offset:3072
	global_load_dwordx4 v[44:47], v[178:179], off
	global_load_dwordx4 v[36:39], v[178:179], off offset:1024
	ds_bpermute_b32 v178, v192, v218
	v_mfma_f32_16x16x32_bf16 v[222:225], v[148:151], v[152:155], v[222:225]
	ds_bpermute_b32 v153, v192, v215
	ds_bpermute_b32 v154, v192, v219
	ds_bpermute_b32 v152, v192, v220
	v_mfma_f32_16x16x32_bf16 v[132:135], v[52:55], v[132:135], 0
	s_and_b64 vcc, exec, s[10:11]
	s_waitcnt lgkmcnt(2)
	v_sub_f32_e32 v153, v153, v178
	v_mul_f32_e32 v153, 0x3fb8aa3b, v153
	v_exp_f32_e32 v178, v153
	v_mfma_f32_16x16x32_bf16 v[132:135], v[32:35], v[136:139], v[132:135]
	s_waitcnt lgkmcnt(1)
	v_mul_f32_e32 v136, v224, v154
	v_mul_f32_e32 v137, v225, v154
	v_mul_f32_e32 v138, v222, v154
	v_mul_f32_e32 v139, v223, v154
	s_mov_b64 s[48:49], -1
	s_nop 3
	v_fma_f32 v132, v178, v132, v138
	v_fma_f32 v133, v178, v133, v139
	v_fma_f32 v134, v178, v134, v136
	v_fma_f32 v135, v178, v135, v137
	s_cbranch_vccnz .LBB0_348
	v_lshl_add_u64 v[136:137], v[166:167], 0, s[44:45]
	s_mov_b64 s[48:49], 0
	global_store_dwordx4 v[136:137], v[132:135], off

.LBB0_352:
	v_mfma_f32_16x16x32_bf16 v[100:103], v[128:131], v[100:103], 0
	s_and_b64 vcc, exec, s[10:11]
	s_mov_b64 s[48:49], -1
	v_mfma_f32_16x16x32_bf16 v[100:103], v[140:143], v[108:111], v[100:103]
	ds_bpermute_b32 v108, v193, v218
	v_mfma_f32_16x16x32_bf16 v[102:105], v[144:147], v[104:107], v[100:103]
	v_mfma_f32_16x16x32_bf16 v[56:59], v[52:55], v[56:59], 0
	s_nop 4
	ds_bpermute_b32 v101, v193, v215
	ds_bpermute_b32 v100, v193, v220
	s_waitcnt lgkmcnt(1)
	v_sub_f32_e32 v101, v101, v108
	v_mfma_f32_16x16x32_bf16 v[88:91], v[148:151], v[88:91], v[102:105]
	v_mul_f32_e32 v101, 0x3fb8aa3b, v101
	s_nop 1
	ds_bpermute_b32 v102, v193, v219
	v_exp_f32_e32 v104, v101
	v_mfma_f32_16x16x32_bf16 v[56:59], v[32:35], v[60:63], v[56:59]
	s_waitcnt lgkmcnt(0)
	s_nop 0
	v_mul_f32_e32 v90, v90, v102
	v_mul_f32_e32 v91, v91, v102
	v_mul_f32_e32 v88, v88, v102
	v_mul_f32_e32 v89, v89, v102
	s_nop 3
	v_fma_f32 v56, v104, v56, v88
	v_fma_f32 v57, v104, v57, v89
	v_fma_f32 v58, v104, v58, v90
	v_fma_f32 v59, v104, v59, v91
	s_cbranch_vccnz .LBB0_354
	v_lshl_add_u64 v[60:61], v[164:165], 0, s[44:45]
	s_mov_b64 s[48:49], 0
	global_store_dwordx4 v[60:61], v[56:59], off

.LBB0_358:
	v_add_f32_e32 v56, v216, v217
	v_add_f32_e32 v88, v210, v216
	v_max_f32_e32 v210, v88, v56
	v_add_f32_e32 v56, v214, v216
	v_sub_f32_e32 v56, v56, v210
	v_mul_f32_e32 v56, 0x3fb8aa3b, v56
	v_exp_f32_e32 v89, v56
	s_mov_b64 s[48:49], -1
	s_and_b64 vcc, exec, s[20:21]
	s_cbranch_vccz .LBB0_360
	ds_bpermute_b32 v56, v194, v89
	ds_bpermute_b32 v57, v195, v89
	ds_bpermute_b32 v60, v196, v89
	ds_bpermute_b32 v61, v197, v89
	v_lshlrev_b32_e32 v58, 16, v52
	v_and_b32_e32 v59, 0xffff0000, v52
	v_lshlrev_b32_e32 v52, 16, v53
	v_and_b32_e32 v53, 0xffff0000, v53
	s_waitcnt lgkmcnt(2)
	v_mul_f32_e32 v56, v58, v56
	v_mul_f32_e32 v57, v59, v57
	s_waitcnt lgkmcnt(0)
	v_mul_f32_e32 v58, v52, v60
	v_mul_f32_e32 v59, v53, v61
	ds_bpermute_b32 v52, v198, v89
	ds_bpermute_b32 v53, v199, v89
	ds_bpermute_b32 v62, v200, v89
	ds_bpermute_b32 v63, v201, v89
	v_lshlrev_b32_e32 v60, 16, v54
	v_and_b32_e32 v61, 0xffff0000, v54
	s_waitcnt lgkmcnt(2)
	v_mul_f32_e32 v60, v60, v52
	v_mul_f32_e32 v61, v61, v53
	v_lshlrev_b32_e32 v52, 16, v55
	v_and_b32_e32 v53, 0xffff0000, v55
	s_waitcnt lgkmcnt(0)
	v_mul_f32_e32 v62, v52, v62
	v_mul_f32_e32 v63, v53, v63
	s_mov_b64 s[48:49], 0

.LBB0_362:
	s_and_b64 vcc, exec, s[10:11]
	s_mov_b64 s[10:11], -1
	v_cvt_pk_bf16_f32 v52, v56, v57
	v_cvt_pk_bf16_f32 v53, v58, v59
	v_cvt_pk_bf16_f32 v54, v60, v61
	v_cvt_pk_bf16_f32 v55, v62, v63
	s_cbranch_vccnz .LBB0_364
	ds_bpermute_b32 v56, v202, v89
	ds_bpermute_b32 v57, v203, v89
	ds_bpermute_b32 v60, v204, v89
	ds_bpermute_b32 v61, v205, v89
	v_lshlrev_b32_e32 v58, 16, v32
	v_and_b32_e32 v59, 0xffff0000, v32
	v_lshlrev_b32_e32 v32, 16, v33
	v_and_b32_e32 v33, 0xffff0000, v33
	s_waitcnt lgkmcnt(2)
	v_mul_f32_e32 v58, v58, v56
	v_mul_f32_e32 v59, v59, v57
	s_waitcnt lgkmcnt(0)
	v_mul_f32_e32 v56, v32, v60
	v_mul_f32_e32 v57, v33, v61
	ds_bpermute_b32 v32, v206, v89
	ds_bpermute_b32 v33, v207, v89
	ds_bpermute_b32 v62, v208, v89
	ds_bpermute_b32 v63, v209, v89
	v_lshlrev_b32_e32 v60, 16, v34
	v_and_b32_e32 v61, 0xffff0000, v34
	s_waitcnt lgkmcnt(2)
	v_mul_f32_e32 v60, v60, v32
	v_mul_f32_e32 v61, v61, v33
	v_lshlrev_b32_e32 v32, 16, v35
	v_and_b32_e32 v33, 0xffff0000, v35
	s_waitcnt lgkmcnt(0)
	v_mul_f32_e32 v62, v32, v62
	v_mul_f32_e32 v63, v33, v63
	s_mov_b64 s[10:11], 0
